# GEMM loops: 24 duplicated back-to-back s_waitcnt lgkmcnt(0) removed
# speedup vs baseline: 1.0053x; 1.0031x over previous
.LBB0_102:
	ds_read_b128 v[156:159], v152
	ds_read_b128 v[160:163], v152 offset:1024
	ds_read_b128 v[164:167], v152 offset:2048
	ds_read_b128 v[168:171], v152 offset:3072
	s_add_i32 vcc_hi, s80, 2
	s_add_u32 s82, s78, 0x80
	s_addc_u32 s81, s79, 0
	s_cmp_eq_u32 s92, s80
	s_cselect_b32 s80, s0, s82
	s_cselect_b32 s81, s1, s81
	s_cselect_b32 s83, s9, vcc_lo
	s_cselect_b32 s82, s8, s73
	v_lshl_add_u64 v[148:149], s[78:79], 0, v[140:141]
	s_add_i32 m0, s84, 0xc000
	ds_read_b128 v[172:175], v153
	ds_read_b128 v[176:179], v153 offset:1024
	ds_read_b128 v[182:185], v153 offset:2048
	ds_read_b128 v[186:189], v153 offset:3072
	ds_read_b128 v[190:193], v153 offset:4096
	ds_read_b128 v[194:197], v153 offset:5120
	ds_read_b128 v[198:201], v153 offset:6144
	ds_read_b128 v[202:205], v153 offset:7168
	global_load_lds_dwordx4 v[148:149], off
	v_lshl_add_u64 v[148:149], s[78:79], 0, v[142:143]
	s_add_i32 m0, s84, 0xe000
	s_nop 0
	global_load_lds_dwordx4 v[148:149], off
	s_waitcnt lgkmcnt(8)
	s_barrier
	s_waitcnt lgkmcnt(0)

	v_mfma_f32_16x16x32_bf16 v[126:129], v[156:159], v[172:175], v[126:129]
	v_mfma_f32_16x16x32_bf16 v[122:125], v[164:167], v[172:175], v[122:125]
	v_mfma_f32_16x16x32_bf16 v[118:121], v[156:159], v[182:185], v[118:121]
	v_mfma_f32_16x16x32_bf16 v[114:117], v[164:167], v[182:185], v[114:117]
	v_mfma_f32_16x16x32_bf16 v[94:97], v[156:159], v[190:193], v[94:97]
	v_mfma_f32_16x16x32_bf16 v[90:93], v[164:167], v[190:193], v[90:93]
	v_mfma_f32_16x16x32_bf16 v[86:89], v[156:159], v[198:201], v[86:89]
	v_mfma_f32_16x16x32_bf16 v[82:85], v[164:167], v[198:201], v[82:85]
	v_mfma_f32_16x16x32_bf16 v[126:129], v[160:163], v[176:179], v[126:129]
	v_mfma_f32_16x16x32_bf16 v[122:125], v[168:171], v[176:179], v[122:125]
	v_mfma_f32_16x16x32_bf16 v[118:121], v[160:163], v[186:189], v[118:121]
	v_mfma_f32_16x16x32_bf16 v[114:117], v[168:171], v[186:189], v[114:117]
	v_mfma_f32_16x16x32_bf16 v[94:97], v[160:163], v[194:197], v[94:97]
	v_mfma_f32_16x16x32_bf16 v[90:93], v[168:171], v[194:197], v[90:93]
	v_mfma_f32_16x16x32_bf16 v[86:89], v[160:163], v[202:205], v[86:89]
	v_mfma_f32_16x16x32_bf16 v[82:85], v[168:171], v[202:205], v[82:85]

	s_barrier
	s_add_i32 s74, s16, s71
	v_lshl_add_u64 v[148:149], s[82:83], 0, v[132:133]
	s_mov_b32 m0, s74
	ds_read_b128 v[206:209], v154
	ds_read_b128 v[210:213], v154 offset:1024
	ds_read_b128 v[214:217], v154 offset:2048
	ds_read_b128 v[218:221], v154 offset:3072
	global_load_lds_dwordx4 v[148:149], off
	v_lshl_add_u64 v[222:223], s[82:83], 0, v[136:137]
	s_add_i32 m0, s74, 0x2000
	s_nop 0
	global_load_lds_dwordx4 v[222:223], off
	s_barrier
	s_waitcnt lgkmcnt(0)

	v_mfma_f32_16x16x32_bf16 v[110:113], v[206:209], v[172:175], v[110:113]
	v_mfma_f32_16x16x32_bf16 v[106:109], v[214:217], v[172:175], v[106:109]
	v_mfma_f32_16x16x32_bf16 v[102:105], v[206:209], v[182:185], v[102:105]
	v_mfma_f32_16x16x32_bf16 v[98:101], v[214:217], v[182:185], v[98:101]
	v_mfma_f32_16x16x32_bf16 v[78:81], v[206:209], v[190:193], v[78:81]
	v_mfma_f32_16x16x32_bf16 v[74:77], v[214:217], v[190:193], v[74:77]
	v_mfma_f32_16x16x32_bf16 v[70:73], v[206:209], v[198:201], v[70:73]
	v_mfma_f32_16x16x32_bf16 v[66:69], v[214:217], v[198:201], v[66:69]
	v_mfma_f32_16x16x32_bf16 v[110:113], v[210:213], v[176:179], v[110:113]
	v_mfma_f32_16x16x32_bf16 v[106:109], v[218:221], v[176:179], v[106:109]
	v_mfma_f32_16x16x32_bf16 v[102:105], v[210:213], v[186:189], v[102:105]
	v_mfma_f32_16x16x32_bf16 v[98:101], v[218:221], v[186:189], v[98:101]
	v_mfma_f32_16x16x32_bf16 v[78:81], v[210:213], v[194:197], v[78:81]
	v_mfma_f32_16x16x32_bf16 v[74:77], v[218:221], v[194:197], v[74:77]
	v_mfma_f32_16x16x32_bf16 v[70:73], v[210:213], v[202:205], v[70:73]
	v_mfma_f32_16x16x32_bf16 v[66:69], v[218:221], v[202:205], v[66:69]

	s_mov_b32 m0, s84
	v_lshl_add_u64 v[224:225], s[80:81], 0, v[130:131]
	s_barrier
	ds_read_b128 v[172:175], v153 offset:16384
	ds_read_b128 v[176:179], v153 offset:17408
	ds_read_b128 v[182:185], v153 offset:18432
	ds_read_b128 v[186:189], v153 offset:19456
	ds_read_b128 v[190:193], v153 offset:20480
	ds_read_b128 v[194:197], v153 offset:21504
	ds_read_b128 v[198:201], v153 offset:22528
	ds_read_b128 v[202:205], v153 offset:23552
	global_load_lds_dwordx4 v[224:225], off
	v_lshl_add_u64 v[226:227], s[80:81], 0, v[134:135]
	s_mov_b32 m0, s85
	s_nop 0
	global_load_lds_dwordx4 v[226:227], off
	s_barrier
	s_waitcnt lgkmcnt(0)

	v_mfma_f32_16x16x32_bf16 v[62:65], v[156:159], v[172:175], v[62:65]
	v_mfma_f32_16x16x32_bf16 v[58:61], v[164:167], v[172:175], v[58:61]
	v_mfma_f32_16x16x32_bf16 v[54:57], v[156:159], v[182:185], v[54:57]
	v_mfma_f32_16x16x32_bf16 v[50:53], v[164:167], v[182:185], v[50:53]
	v_mfma_f32_16x16x32_bf16 v[30:33], v[156:159], v[190:193], v[30:33]
	v_mfma_f32_16x16x32_bf16 v[26:29], v[164:167], v[190:193], v[26:29]
	v_mfma_f32_16x16x32_bf16 v[22:25], v[156:159], v[198:201], v[22:25]
	v_mfma_f32_16x16x32_bf16 v[18:21], v[164:167], v[198:201], v[18:21]
	v_mfma_f32_16x16x32_bf16 v[62:65], v[160:163], v[176:179], v[62:65]
	v_mfma_f32_16x16x32_bf16 v[58:61], v[168:171], v[176:179], v[58:61]
	v_mfma_f32_16x16x32_bf16 v[54:57], v[160:163], v[186:189], v[54:57]
	v_mfma_f32_16x16x32_bf16 v[50:53], v[168:171], v[186:189], v[50:53]
	v_mfma_f32_16x16x32_bf16 v[30:33], v[160:163], v[194:197], v[30:33]
	v_mfma_f32_16x16x32_bf16 v[26:29], v[168:171], v[194:197], v[26:29]
	v_mfma_f32_16x16x32_bf16 v[22:25], v[160:163], v[202:205], v[22:25]
	v_mfma_f32_16x16x32_bf16 v[18:21], v[168:171], v[202:205], v[18:21]

	s_barrier
	s_add_u32 s82, s82, s10
	s_addc_u32 s83, s83, s11
	s_add_i32 s74, s70, s71
	v_lshl_add_u64 v[228:229], s[82:83], 0, v[132:133]
	s_mov_b32 m0, s74
	v_lshl_add_u64 v[230:231], s[82:83], 0, v[136:137]
	global_load_lds_dwordx4 v[228:229], off
	s_add_i32 m0, s74, 0x2000
	s_nop 0
	global_load_lds_dwordx4 v[230:231], off
	s_waitcnt vmcnt(6)
	s_barrier

	v_mfma_f32_16x16x32_bf16 v[46:49], v[206:209], v[172:175], v[46:49]
	v_mfma_f32_16x16x32_bf16 v[42:45], v[214:217], v[172:175], v[42:45]
	v_mfma_f32_16x16x32_bf16 v[38:41], v[206:209], v[182:185], v[38:41]
	v_mfma_f32_16x16x32_bf16 v[34:37], v[214:217], v[182:185], v[34:37]
	v_mfma_f32_16x16x32_bf16 v[14:17], v[206:209], v[190:193], v[14:17]
	v_mfma_f32_16x16x32_bf16 v[10:13], v[214:217], v[190:193], v[10:13]
	v_mfma_f32_16x16x32_bf16 v[6:9], v[206:209], v[198:201], v[6:9]
	v_mfma_f32_16x16x32_bf16 v[2:5], v[214:217], v[198:201], v[2:5]
	v_mfma_f32_16x16x32_bf16 v[46:49], v[210:213], v[176:179], v[46:49]
	v_mfma_f32_16x16x32_bf16 v[42:45], v[218:221], v[176:179], v[42:45]
	v_mfma_f32_16x16x32_bf16 v[38:41], v[210:213], v[186:189], v[38:41]
	v_mfma_f32_16x16x32_bf16 v[34:37], v[218:221], v[186:189], v[34:37]
	v_mfma_f32_16x16x32_bf16 v[14:17], v[210:213], v[194:197], v[14:17]
	v_mfma_f32_16x16x32_bf16 v[10:13], v[218:221], v[194:197], v[10:13]
	v_mfma_f32_16x16x32_bf16 v[6:9], v[210:213], v[202:205], v[6:9]
	v_mfma_f32_16x16x32_bf16 v[2:5], v[218:221], v[202:205], v[2:5]

	s_add_i32 s74, 0, 0x18000
	v_add_u32_e32 v155, s74, v150
	s_barrier
	ds_read_b128 v[156:159], v155
	ds_read_b128 v[160:163], v155 offset:1024
	ds_read_b128 v[164:167], v155 offset:2048
	ds_read_b128 v[168:171], v155 offset:3072
	s_add_u32 s80, s80, s10
	s_addc_u32 s81, s81, s11
	s_mov_b32 m0, s86
	v_lshl_add_u64 v[206:207], s[80:81], 0, v[130:131]
	ds_read_b128 v[172:175], v153 offset:32768
	ds_read_b128 v[176:179], v153 offset:33792
	ds_read_b128 v[182:185], v153 offset:34816
	ds_read_b128 v[186:189], v153 offset:35840
	ds_read_b128 v[190:193], v153 offset:36864
	ds_read_b128 v[194:197], v153 offset:37888
	ds_read_b128 v[198:201], v153 offset:38912
	ds_read_b128 v[202:205], v153 offset:39936
	global_load_lds_dwordx4 v[206:207], off
	v_lshl_add_u64 v[206:207], s[80:81], 0, v[134:135]
	s_mov_b32 m0, s87
	s_nop 0
	global_load_lds_dwordx4 v[206:207], off
	s_waitcnt lgkmcnt(8)
	s_barrier
	s_waitcnt lgkmcnt(0)

	v_mfma_f32_16x16x32_bf16 v[126:129], v[156:159], v[172:175], v[126:129]
	v_mfma_f32_16x16x32_bf16 v[122:125], v[164:167], v[172:175], v[122:125]
	v_mfma_f32_16x16x32_bf16 v[118:121], v[156:159], v[182:185], v[118:121]
	v_mfma_f32_16x16x32_bf16 v[114:117], v[164:167], v[182:185], v[114:117]
	v_mfma_f32_16x16x32_bf16 v[94:97], v[156:159], v[190:193], v[94:97]
	v_mfma_f32_16x16x32_bf16 v[90:93], v[164:167], v[190:193], v[90:93]
	v_mfma_f32_16x16x32_bf16 v[86:89], v[156:159], v[198:201], v[86:89]
	v_mfma_f32_16x16x32_bf16 v[82:85], v[164:167], v[198:201], v[82:85]
	v_mfma_f32_16x16x32_bf16 v[126:129], v[160:163], v[176:179], v[126:129]
	v_mfma_f32_16x16x32_bf16 v[122:125], v[168:171], v[176:179], v[122:125]
	v_mfma_f32_16x16x32_bf16 v[118:121], v[160:163], v[186:189], v[118:121]
	v_mfma_f32_16x16x32_bf16 v[114:117], v[168:171], v[186:189], v[114:117]
	v_mfma_f32_16x16x32_bf16 v[94:97], v[160:163], v[194:197], v[94:97]
	v_mfma_f32_16x16x32_bf16 v[90:93], v[168:171], v[194:197], v[90:93]
	v_mfma_f32_16x16x32_bf16 v[86:89], v[160:163], v[202:205], v[86:89]
	v_mfma_f32_16x16x32_bf16 v[82:85], v[168:171], v[202:205], v[82:85]

	s_barrier
	s_add_i32 s75, 0, 0x1c000
	s_add_i32 s74, s74, s71
	v_add_u32_e32 v155, s75, v150
	v_lshl_add_u64 v[148:149], v[148:149], 0, s[14:15]
	s_mov_b32 m0, s74
	ds_read_b128 v[206:209], v155
	ds_read_b128 v[210:213], v155 offset:1024
	ds_read_b128 v[214:217], v155 offset:2048
	ds_read_b128 v[218:221], v155 offset:3072
	global_load_lds_dwordx4 v[148:149], off
	v_lshl_add_u64 v[148:149], v[222:223], 0, s[14:15]
	s_add_i32 m0, s74, 0x2000
	s_nop 0
	global_load_lds_dwordx4 v[148:149], off
	s_barrier
	s_waitcnt lgkmcnt(0)

	v_mfma_f32_16x16x32_bf16 v[110:113], v[206:209], v[172:175], v[110:113]
	v_mfma_f32_16x16x32_bf16 v[106:109], v[214:217], v[172:175], v[106:109]
	v_mfma_f32_16x16x32_bf16 v[102:105], v[206:209], v[182:185], v[102:105]
	v_mfma_f32_16x16x32_bf16 v[98:101], v[214:217], v[182:185], v[98:101]
	v_mfma_f32_16x16x32_bf16 v[78:81], v[206:209], v[190:193], v[78:81]
	v_mfma_f32_16x16x32_bf16 v[74:77], v[214:217], v[190:193], v[74:77]
	v_mfma_f32_16x16x32_bf16 v[70:73], v[206:209], v[198:201], v[70:73]
	v_mfma_f32_16x16x32_bf16 v[66:69], v[214:217], v[198:201], v[66:69]
	v_mfma_f32_16x16x32_bf16 v[110:113], v[210:213], v[176:179], v[110:113]
	v_mfma_f32_16x16x32_bf16 v[106:109], v[218:221], v[176:179], v[106:109]
	v_mfma_f32_16x16x32_bf16 v[102:105], v[210:213], v[186:189], v[102:105]
	v_mfma_f32_16x16x32_bf16 v[98:101], v[218:221], v[186:189], v[98:101]
	v_mfma_f32_16x16x32_bf16 v[78:81], v[210:213], v[194:197], v[78:81]
	v_mfma_f32_16x16x32_bf16 v[74:77], v[218:221], v[194:197], v[74:77]
	v_mfma_f32_16x16x32_bf16 v[70:73], v[210:213], v[202:205], v[70:73]
	v_mfma_f32_16x16x32_bf16 v[66:69], v[218:221], v[202:205], v[66:69]

	s_mov_b32 m0, s89
	v_lshl_add_u64 v[148:149], v[224:225], 0, s[14:15]
	s_barrier
	ds_read_b128 v[172:175], v153 offset:49152
	ds_read_b128 v[176:179], v153 offset:50176
	ds_read_b128 v[182:185], v153 offset:51200
	ds_read_b128 v[186:189], v153 offset:52224
	ds_read_b128 v[190:193], v153 offset:53248
	ds_read_b128 v[194:197], v153 offset:54272
	ds_read_b128 v[198:201], v153 offset:55296
	ds_read_b128 v[202:205], v153 offset:56320
	global_load_lds_dwordx4 v[148:149], off
	v_lshl_add_u64 v[148:149], v[226:227], 0, s[14:15]
	s_mov_b32 m0, s90
	s_nop 0
	global_load_lds_dwordx4 v[148:149], off
	s_barrier
	s_waitcnt lgkmcnt(0)

	v_mfma_f32_16x16x32_bf16 v[62:65], v[156:159], v[172:175], v[62:65]
	v_mfma_f32_16x16x32_bf16 v[58:61], v[164:167], v[172:175], v[58:61]
	v_mfma_f32_16x16x32_bf16 v[54:57], v[156:159], v[182:185], v[54:57]
	v_mfma_f32_16x16x32_bf16 v[50:53], v[164:167], v[182:185], v[50:53]
	v_mfma_f32_16x16x32_bf16 v[30:33], v[156:159], v[190:193], v[30:33]
	v_mfma_f32_16x16x32_bf16 v[26:29], v[164:167], v[190:193], v[26:29]
	v_mfma_f32_16x16x32_bf16 v[22:25], v[156:159], v[198:201], v[22:25]
	v_mfma_f32_16x16x32_bf16 v[18:21], v[164:167], v[198:201], v[18:21]
	v_mfma_f32_16x16x32_bf16 v[62:65], v[160:163], v[176:179], v[62:65]
	v_mfma_f32_16x16x32_bf16 v[58:61], v[168:171], v[176:179], v[58:61]
	v_mfma_f32_16x16x32_bf16 v[54:57], v[160:163], v[186:189], v[54:57]
	v_mfma_f32_16x16x32_bf16 v[50:53], v[168:171], v[186:189], v[50:53]
	v_mfma_f32_16x16x32_bf16 v[30:33], v[160:163], v[194:197], v[30:33]
	v_mfma_f32_16x16x32_bf16 v[26:29], v[168:171], v[194:197], v[26:29]
	v_mfma_f32_16x16x32_bf16 v[22:25], v[160:163], v[202:205], v[22:25]
	v_mfma_f32_16x16x32_bf16 v[18:21], v[168:171], v[202:205], v[18:21]

	s_barrier
	s_add_i32 s74, s75, s71
	v_lshl_add_u64 v[148:149], v[228:229], 0, s[14:15]
	s_mov_b32 m0, s74
	s_nop 0
	global_load_lds_dwordx4 v[148:149], off
	v_lshl_add_u64 v[148:149], v[230:231], 0, s[14:15]
	s_add_i32 m0, s74, 0x2000
	s_nop 0
	global_load_lds_dwordx4 v[148:149], off
	s_waitcnt vmcnt(6)
	s_barrier

	v_mfma_f32_16x16x32_bf16 v[46:49], v[206:209], v[172:175], v[46:49]
	v_mfma_f32_16x16x32_bf16 v[42:45], v[214:217], v[172:175], v[42:45]
	v_mfma_f32_16x16x32_bf16 v[38:41], v[206:209], v[182:185], v[38:41]
	v_mfma_f32_16x16x32_bf16 v[34:37], v[214:217], v[182:185], v[34:37]
	v_mfma_f32_16x16x32_bf16 v[14:17], v[206:209], v[190:193], v[14:17]
	v_mfma_f32_16x16x32_bf16 v[10:13], v[214:217], v[190:193], v[10:13]
	v_mfma_f32_16x16x32_bf16 v[6:9], v[206:209], v[198:201], v[6:9]
	v_mfma_f32_16x16x32_bf16 v[2:5], v[214:217], v[198:201], v[2:5]
	v_mfma_f32_16x16x32_bf16 v[46:49], v[210:213], v[176:179], v[46:49]
	v_mfma_f32_16x16x32_bf16 v[42:45], v[218:221], v[176:179], v[42:45]
	v_mfma_f32_16x16x32_bf16 v[38:41], v[210:213], v[186:189], v[38:41]
	v_mfma_f32_16x16x32_bf16 v[34:37], v[218:221], v[186:189], v[34:37]
	v_mfma_f32_16x16x32_bf16 v[14:17], v[210:213], v[194:197], v[14:17]
	v_mfma_f32_16x16x32_bf16 v[10:13], v[218:221], v[194:197], v[10:13]
	v_mfma_f32_16x16x32_bf16 v[6:9], v[210:213], v[202:205], v[6:9]
	v_mfma_f32_16x16x32_bf16 v[2:5], v[218:221], v[202:205], v[2:5]

	s_add_u32 s78, s78, 0x100
	s_addc_u32 s79, s79, 0
	s_add_u32 s73, s73, 0x100
	s_addc_u32 vcc_lo, vcc_lo, 0
	s_cmp_ge_i32 vcc_hi, s91
	s_mov_b32 s80, vcc_hi
	s_barrier
	s_cbranch_scc0 .LBB0_102

.LBB0_470:
	ds_read_b128 v[146:149], v160
	ds_read_b128 v[150:153], v160 offset:1024
	ds_read_b128 v[154:157], v160 offset:2048
	ds_read_b128 v[164:167], v160 offset:3072
	s_add_i32 s90, s62, 2
	s_add_u32 s72, s50, 0x80
	s_addc_u32 s63, s51, 0
	s_cmp_eq_u32 s78, s62
	s_cselect_b32 s62, s0, s72
	s_cselect_b32 s63, s1, s63
	s_cselect_b32 s73, s7, s89
	s_cselect_b32 s72, s6, s88
	v_lshl_add_u64 v[202:203], s[50:51], 0, v[138:139]
	s_add_i32 m0, s69, 0xc000
	ds_read_b128 v[168:171], v161
	ds_read_b128 v[172:175], v161 offset:1024
	ds_read_b128 v[176:179], v161 offset:2048
	ds_read_b128 v[182:185], v161 offset:3072
	ds_read_b128 v[186:189], v161 offset:4096
	ds_read_b128 v[190:193], v161 offset:5120
	ds_read_b128 v[194:197], v161 offset:6144
	ds_read_b128 v[198:201], v161 offset:7168
	global_load_lds_dwordx4 v[202:203], off
	v_lshl_add_u64 v[202:203], s[50:51], 0, v[140:141]
	s_add_i32 m0, s69, 0xe000
	s_nop 0
	global_load_lds_dwordx4 v[202:203], off
	s_waitcnt lgkmcnt(8)
	s_barrier
	s_waitcnt lgkmcnt(0)

	v_mfma_f32_16x16x32_bf16 v[126:129], v[146:149], v[168:171], v[126:129]
	v_mfma_f32_16x16x32_bf16 v[122:125], v[154:157], v[168:171], v[122:125]
	v_mfma_f32_16x16x32_bf16 v[110:113], v[146:149], v[176:179], v[110:113]
	v_mfma_f32_16x16x32_bf16 v[106:109], v[154:157], v[176:179], v[106:109]
	v_mfma_f32_16x16x32_bf16 v[94:97], v[146:149], v[186:189], v[94:97]
	v_mfma_f32_16x16x32_bf16 v[90:93], v[154:157], v[186:189], v[90:93]
	v_mfma_f32_16x16x32_bf16 v[78:81], v[146:149], v[194:197], v[78:81]
	v_mfma_f32_16x16x32_bf16 v[74:77], v[154:157], v[194:197], v[74:77]
	v_mfma_f32_16x16x32_bf16 v[126:129], v[150:153], v[172:175], v[126:129]
	v_mfma_f32_16x16x32_bf16 v[122:125], v[164:167], v[172:175], v[122:125]
	v_mfma_f32_16x16x32_bf16 v[110:113], v[150:153], v[182:185], v[110:113]
	v_mfma_f32_16x16x32_bf16 v[106:109], v[164:167], v[182:185], v[106:109]
	v_mfma_f32_16x16x32_bf16 v[94:97], v[150:153], v[190:193], v[94:97]
	v_mfma_f32_16x16x32_bf16 v[90:93], v[164:167], v[190:193], v[90:93]
	v_mfma_f32_16x16x32_bf16 v[78:81], v[150:153], v[198:201], v[78:81]
	v_mfma_f32_16x16x32_bf16 v[74:77], v[164:167], v[198:201], v[74:77]

	s_barrier
	s_add_i32 s91, s81, s68
	v_lshl_add_u64 v[218:219], s[72:73], 0, v[132:133]
	s_mov_b32 m0, s91
	ds_read_b128 v[202:205], v162
	ds_read_b128 v[206:209], v162 offset:1024
	ds_read_b128 v[210:213], v162 offset:2048
	ds_read_b128 v[214:217], v162 offset:3072
	global_load_lds_dwordx4 v[218:219], off
	v_lshl_add_u64 v[220:221], s[72:73], 0, v[136:137]
	s_add_i32 m0, s91, 0x2000
	s_nop 0
	global_load_lds_dwordx4 v[220:221], off
	s_barrier
	s_waitcnt lgkmcnt(0)

	v_mfma_f32_16x16x32_bf16 v[118:121], v[202:205], v[168:171], v[118:121]
	v_mfma_f32_16x16x32_bf16 v[114:117], v[210:213], v[168:171], v[114:117]
	v_mfma_f32_16x16x32_bf16 v[102:105], v[202:205], v[176:179], v[102:105]
	v_mfma_f32_16x16x32_bf16 v[98:101], v[210:213], v[176:179], v[98:101]
	v_mfma_f32_16x16x32_bf16 v[86:89], v[202:205], v[186:189], v[86:89]
	v_mfma_f32_16x16x32_bf16 v[82:85], v[210:213], v[186:189], v[82:85]
	v_mfma_f32_16x16x32_bf16 v[70:73], v[202:205], v[194:197], v[70:73]
	v_mfma_f32_16x16x32_bf16 v[66:69], v[210:213], v[194:197], v[66:69]
	v_mfma_f32_16x16x32_bf16 v[118:121], v[206:209], v[172:175], v[118:121]
	v_mfma_f32_16x16x32_bf16 v[114:117], v[214:217], v[172:175], v[114:117]
	v_mfma_f32_16x16x32_bf16 v[102:105], v[206:209], v[182:185], v[102:105]
	v_mfma_f32_16x16x32_bf16 v[98:101], v[214:217], v[182:185], v[98:101]
	v_mfma_f32_16x16x32_bf16 v[86:89], v[206:209], v[190:193], v[86:89]
	v_mfma_f32_16x16x32_bf16 v[82:85], v[214:217], v[190:193], v[82:85]
	v_mfma_f32_16x16x32_bf16 v[70:73], v[206:209], v[198:201], v[70:73]
	v_mfma_f32_16x16x32_bf16 v[66:69], v[214:217], v[198:201], v[66:69]

	s_mov_b32 m0, s69
	v_lshl_add_u64 v[222:223], s[62:63], 0, v[130:131]
	s_barrier
	ds_read_b128 v[168:171], v161 offset:16384
	ds_read_b128 v[172:175], v161 offset:17408
	ds_read_b128 v[176:179], v161 offset:18432
	ds_read_b128 v[182:185], v161 offset:19456
	ds_read_b128 v[186:189], v161 offset:20480
	ds_read_b128 v[190:193], v161 offset:21504
	ds_read_b128 v[194:197], v161 offset:22528
	ds_read_b128 v[198:201], v161 offset:23552
	global_load_lds_dwordx4 v[222:223], off
	v_lshl_add_u64 v[224:225], s[62:63], 0, v[134:135]
	s_mov_b32 m0, s70
	s_nop 0
	global_load_lds_dwordx4 v[224:225], off
	s_barrier
	s_waitcnt lgkmcnt(0)

	v_mfma_f32_16x16x32_bf16 v[62:65], v[146:149], v[168:171], v[62:65]
	v_mfma_f32_16x16x32_bf16 v[58:61], v[154:157], v[168:171], v[58:61]
	v_mfma_f32_16x16x32_bf16 v[46:49], v[146:149], v[176:179], v[46:49]
	v_mfma_f32_16x16x32_bf16 v[42:45], v[154:157], v[176:179], v[42:45]
	v_mfma_f32_16x16x32_bf16 v[30:33], v[146:149], v[186:189], v[30:33]
	v_mfma_f32_16x16x32_bf16 v[26:29], v[154:157], v[186:189], v[26:29]
	v_mfma_f32_16x16x32_bf16 v[14:17], v[146:149], v[194:197], v[14:17]
	v_mfma_f32_16x16x32_bf16 v[10:13], v[154:157], v[194:197], v[10:13]
	v_mfma_f32_16x16x32_bf16 v[62:65], v[150:153], v[172:175], v[62:65]
	v_mfma_f32_16x16x32_bf16 v[58:61], v[164:167], v[172:175], v[58:61]
	v_mfma_f32_16x16x32_bf16 v[46:49], v[150:153], v[182:185], v[46:49]
	v_mfma_f32_16x16x32_bf16 v[42:45], v[164:167], v[182:185], v[42:45]
	v_mfma_f32_16x16x32_bf16 v[30:33], v[150:153], v[190:193], v[30:33]
	v_mfma_f32_16x16x32_bf16 v[26:29], v[164:167], v[190:193], v[26:29]
	v_mfma_f32_16x16x32_bf16 v[14:17], v[150:153], v[198:201], v[14:17]
	v_mfma_f32_16x16x32_bf16 v[10:13], v[164:167], v[198:201], v[10:13]

	s_barrier
	s_add_u32 s72, s72, s10
	s_addc_u32 s73, s73, s11
	s_add_i32 s91, s82, s68
	v_lshl_add_u64 v[226:227], s[72:73], 0, v[132:133]
	s_mov_b32 m0, s91
	v_lshl_add_u64 v[228:229], s[72:73], 0, v[136:137]
	global_load_lds_dwordx4 v[226:227], off
	s_add_i32 m0, s91, 0x2000
	s_nop 0
	global_load_lds_dwordx4 v[228:229], off
	s_waitcnt vmcnt(6)
	s_barrier

	v_mfma_f32_16x16x32_bf16 v[54:57], v[202:205], v[168:171], v[54:57]
	v_mfma_f32_16x16x32_bf16 v[50:53], v[210:213], v[168:171], v[50:53]
	v_mfma_f32_16x16x32_bf16 v[38:41], v[202:205], v[176:179], v[38:41]
	v_mfma_f32_16x16x32_bf16 v[34:37], v[210:213], v[176:179], v[34:37]
	v_mfma_f32_16x16x32_bf16 v[22:25], v[202:205], v[186:189], v[22:25]
	v_mfma_f32_16x16x32_bf16 v[18:21], v[210:213], v[186:189], v[18:21]
	v_mfma_f32_16x16x32_bf16 v[6:9], v[202:205], v[194:197], v[6:9]
	v_mfma_f32_16x16x32_bf16 v[2:5], v[210:213], v[194:197], v[2:5]
	v_mfma_f32_16x16x32_bf16 v[54:57], v[206:209], v[172:175], v[54:57]
	v_mfma_f32_16x16x32_bf16 v[50:53], v[214:217], v[172:175], v[50:53]
	v_mfma_f32_16x16x32_bf16 v[38:41], v[206:209], v[182:185], v[38:41]
	v_mfma_f32_16x16x32_bf16 v[34:37], v[214:217], v[182:185], v[34:37]
	v_mfma_f32_16x16x32_bf16 v[22:25], v[206:209], v[190:193], v[22:25]
	v_mfma_f32_16x16x32_bf16 v[18:21], v[214:217], v[190:193], v[18:21]
	v_mfma_f32_16x16x32_bf16 v[6:9], v[206:209], v[198:201], v[6:9]
	v_mfma_f32_16x16x32_bf16 v[2:5], v[214:217], v[198:201], v[2:5]

	s_add_i32 s72, 0, 0x18000
	v_add_u32_e32 v163, s72, v158
	s_barrier
	ds_read_b128 v[146:149], v163
	ds_read_b128 v[150:153], v163 offset:1024
	ds_read_b128 v[154:157], v163 offset:2048
	ds_read_b128 v[164:167], v163 offset:3072
	s_add_u32 s62, s62, s10
	s_addc_u32 s63, s63, s11
	s_mov_b32 m0, s3
	v_lshl_add_u64 v[202:203], s[62:63], 0, v[130:131]
	ds_read_b128 v[168:171], v161 offset:32768
	ds_read_b128 v[172:175], v161 offset:33792
	ds_read_b128 v[176:179], v161 offset:34816
	ds_read_b128 v[182:185], v161 offset:35840
	ds_read_b128 v[186:189], v161 offset:36864
	ds_read_b128 v[190:193], v161 offset:37888
	ds_read_b128 v[194:197], v161 offset:38912
	ds_read_b128 v[198:201], v161 offset:39936
	global_load_lds_dwordx4 v[202:203], off
	v_lshl_add_u64 v[202:203], s[62:63], 0, v[134:135]
	s_mov_b32 m0, s71
	s_nop 0
	global_load_lds_dwordx4 v[202:203], off
	s_waitcnt lgkmcnt(8)
	s_barrier
	s_waitcnt lgkmcnt(0)

	v_mfma_f32_16x16x32_bf16 v[126:129], v[146:149], v[168:171], v[126:129]
	v_mfma_f32_16x16x32_bf16 v[122:125], v[154:157], v[168:171], v[122:125]
	v_mfma_f32_16x16x32_bf16 v[110:113], v[146:149], v[176:179], v[110:113]
	v_mfma_f32_16x16x32_bf16 v[106:109], v[154:157], v[176:179], v[106:109]
	v_mfma_f32_16x16x32_bf16 v[94:97], v[146:149], v[186:189], v[94:97]
	v_mfma_f32_16x16x32_bf16 v[90:93], v[154:157], v[186:189], v[90:93]
	v_mfma_f32_16x16x32_bf16 v[78:81], v[146:149], v[194:197], v[78:81]
	v_mfma_f32_16x16x32_bf16 v[74:77], v[154:157], v[194:197], v[74:77]
	v_mfma_f32_16x16x32_bf16 v[126:129], v[150:153], v[172:175], v[126:129]
	v_mfma_f32_16x16x32_bf16 v[122:125], v[164:167], v[172:175], v[122:125]
	v_mfma_f32_16x16x32_bf16 v[110:113], v[150:153], v[182:185], v[110:113]
	v_mfma_f32_16x16x32_bf16 v[106:109], v[164:167], v[182:185], v[106:109]
	v_mfma_f32_16x16x32_bf16 v[94:97], v[150:153], v[190:193], v[94:97]
	v_mfma_f32_16x16x32_bf16 v[90:93], v[164:167], v[190:193], v[90:93]
	v_mfma_f32_16x16x32_bf16 v[78:81], v[150:153], v[198:201], v[78:81]
	v_mfma_f32_16x16x32_bf16 v[74:77], v[164:167], v[198:201], v[74:77]

	s_barrier
	s_add_i32 s62, 0, 0x1c000
	s_add_i32 s63, s72, s68
	v_add_u32_e32 v163, s62, v158
	v_lshl_add_u64 v[218:219], v[218:219], 0, s[14:15]
	s_mov_b32 m0, s63
	ds_read_b128 v[202:205], v163
	ds_read_b128 v[206:209], v163 offset:1024
	ds_read_b128 v[210:213], v163 offset:2048
	ds_read_b128 v[214:217], v163 offset:3072
	global_load_lds_dwordx4 v[218:219], off
	v_lshl_add_u64 v[218:219], v[220:221], 0, s[14:15]
	s_add_i32 m0, s63, 0x2000
	s_nop 0
	global_load_lds_dwordx4 v[218:219], off
	s_barrier
	s_waitcnt lgkmcnt(0)

	v_mfma_f32_16x16x32_bf16 v[118:121], v[202:205], v[168:171], v[118:121]
	v_mfma_f32_16x16x32_bf16 v[114:117], v[210:213], v[168:171], v[114:117]
	v_mfma_f32_16x16x32_bf16 v[102:105], v[202:205], v[176:179], v[102:105]
	v_mfma_f32_16x16x32_bf16 v[98:101], v[210:213], v[176:179], v[98:101]
	v_mfma_f32_16x16x32_bf16 v[86:89], v[202:205], v[186:189], v[86:89]
	v_mfma_f32_16x16x32_bf16 v[82:85], v[210:213], v[186:189], v[82:85]
	v_mfma_f32_16x16x32_bf16 v[70:73], v[202:205], v[194:197], v[70:73]
	v_mfma_f32_16x16x32_bf16 v[66:69], v[210:213], v[194:197], v[66:69]
	v_mfma_f32_16x16x32_bf16 v[118:121], v[206:209], v[172:175], v[118:121]
	v_mfma_f32_16x16x32_bf16 v[114:117], v[214:217], v[172:175], v[114:117]
	v_mfma_f32_16x16x32_bf16 v[102:105], v[206:209], v[182:185], v[102:105]
	v_mfma_f32_16x16x32_bf16 v[98:101], v[214:217], v[182:185], v[98:101]
	v_mfma_f32_16x16x32_bf16 v[86:89], v[206:209], v[190:193], v[86:89]
	v_mfma_f32_16x16x32_bf16 v[82:85], v[214:217], v[190:193], v[82:85]
	v_mfma_f32_16x16x32_bf16 v[70:73], v[206:209], v[198:201], v[70:73]
	v_mfma_f32_16x16x32_bf16 v[66:69], v[214:217], v[198:201], v[66:69]

	s_mov_b32 m0, s75
	v_lshl_add_u64 v[218:219], v[222:223], 0, s[14:15]
	s_barrier
	ds_read_b128 v[168:171], v161 offset:49152
	ds_read_b128 v[172:175], v161 offset:50176
	ds_read_b128 v[176:179], v161 offset:51200
	ds_read_b128 v[182:185], v161 offset:52224
	ds_read_b128 v[186:189], v161 offset:53248
	ds_read_b128 v[190:193], v161 offset:54272
	ds_read_b128 v[194:197], v161 offset:55296
	ds_read_b128 v[198:201], v161 offset:56320
	global_load_lds_dwordx4 v[218:219], off
	v_lshl_add_u64 v[218:219], v[224:225], 0, s[14:15]
	s_mov_b32 m0, s76
	s_nop 0
	global_load_lds_dwordx4 v[218:219], off
	s_barrier
	s_waitcnt lgkmcnt(0)

	v_mfma_f32_16x16x32_bf16 v[62:65], v[146:149], v[168:171], v[62:65]
	v_mfma_f32_16x16x32_bf16 v[58:61], v[154:157], v[168:171], v[58:61]
	v_mfma_f32_16x16x32_bf16 v[46:49], v[146:149], v[176:179], v[46:49]
	v_mfma_f32_16x16x32_bf16 v[42:45], v[154:157], v[176:179], v[42:45]
	v_mfma_f32_16x16x32_bf16 v[30:33], v[146:149], v[186:189], v[30:33]
	v_mfma_f32_16x16x32_bf16 v[26:29], v[154:157], v[186:189], v[26:29]
	v_mfma_f32_16x16x32_bf16 v[14:17], v[146:149], v[194:197], v[14:17]
	v_mfma_f32_16x16x32_bf16 v[10:13], v[154:157], v[194:197], v[10:13]
	v_mfma_f32_16x16x32_bf16 v[62:65], v[150:153], v[172:175], v[62:65]
	v_mfma_f32_16x16x32_bf16 v[58:61], v[164:167], v[172:175], v[58:61]
	v_mfma_f32_16x16x32_bf16 v[46:49], v[150:153], v[182:185], v[46:49]
	v_mfma_f32_16x16x32_bf16 v[42:45], v[164:167], v[182:185], v[42:45]
	v_mfma_f32_16x16x32_bf16 v[30:33], v[150:153], v[190:193], v[30:33]
	v_mfma_f32_16x16x32_bf16 v[26:29], v[164:167], v[190:193], v[26:29]
	v_mfma_f32_16x16x32_bf16 v[14:17], v[150:153], v[198:201], v[14:17]
	v_mfma_f32_16x16x32_bf16 v[10:13], v[164:167], v[198:201], v[10:13]

	s_barrier
	s_add_i32 s62, s62, s68
	v_lshl_add_u64 v[146:147], v[226:227], 0, s[14:15]
	s_mov_b32 m0, s62
	s_nop 0
	global_load_lds_dwordx4 v[146:147], off
	v_lshl_add_u64 v[146:147], v[228:229], 0, s[14:15]
	s_add_i32 m0, s62, 0x2000
	s_nop 0
	global_load_lds_dwordx4 v[146:147], off
	s_waitcnt vmcnt(6)
	s_barrier

	v_mfma_f32_16x16x32_bf16 v[54:57], v[202:205], v[168:171], v[54:57]
	v_mfma_f32_16x16x32_bf16 v[50:53], v[210:213], v[168:171], v[50:53]
	v_mfma_f32_16x16x32_bf16 v[38:41], v[202:205], v[176:179], v[38:41]
	v_mfma_f32_16x16x32_bf16 v[34:37], v[210:213], v[176:179], v[34:37]
	v_mfma_f32_16x16x32_bf16 v[22:25], v[202:205], v[186:189], v[22:25]
	v_mfma_f32_16x16x32_bf16 v[18:21], v[210:213], v[186:189], v[18:21]
	v_mfma_f32_16x16x32_bf16 v[6:9], v[202:205], v[194:197], v[6:9]
	v_mfma_f32_16x16x32_bf16 v[2:5], v[210:213], v[194:197], v[2:5]
	v_mfma_f32_16x16x32_bf16 v[54:57], v[206:209], v[172:175], v[54:57]
	v_mfma_f32_16x16x32_bf16 v[50:53], v[214:217], v[172:175], v[50:53]
	v_mfma_f32_16x16x32_bf16 v[38:41], v[206:209], v[182:185], v[38:41]
	v_mfma_f32_16x16x32_bf16 v[34:37], v[214:217], v[182:185], v[34:37]
	v_mfma_f32_16x16x32_bf16 v[22:25], v[206:209], v[190:193], v[22:25]
	v_mfma_f32_16x16x32_bf16 v[18:21], v[214:217], v[190:193], v[18:21]
	v_mfma_f32_16x16x32_bf16 v[6:9], v[206:209], v[198:201], v[6:9]
	v_mfma_f32_16x16x32_bf16 v[2:5], v[214:217], v[198:201], v[2:5]

	s_add_u32 s50, s50, 0x100
	s_addc_u32 s51, s51, 0
	s_add_u32 s88, s88, 0x100
	s_addc_u32 s89, s89, 0
	s_cmp_ge_i32 s90, s77
	s_mov_b32 s62, s90
	s_barrier
	s_cbranch_scc0 .LBB0_470

.LBB0_678:
	s_add_i32 s68, s68, 2
	s_and_b64 s[64:65], exec, s[64:65]
	s_cselect_b32 s65, s53, s97
	s_cselect_b32 s64, s52, s96
	s_add_i32 s3, 0, 0x10000
	v_add_u32_e32 v1, s3, v196
	ds_read_b128 v[132:135], v1
	ds_read_b128 v[136:139], v1 offset:1024
	ds_read_b128 v[140:143], v1 offset:2048
	ds_read_b128 v[144:147], v1 offset:3072
	s_add_u32 s62, s62, 0x20000
	s_addc_u32 s63, s63, 0
	v_lshl_add_u64 v[2:3], s[62:63], 0, v[182:183]
	s_add_i32 m0, s70, 0xc000
	ds_read_b128 v[148:151], v197
	ds_read_b128 v[152:155], v197 offset:1024
	ds_read_b128 v[156:159], v197 offset:2048
	ds_read_b128 v[160:163], v197 offset:3072
	ds_read_b128 v[164:167], v197 offset:4096
	ds_read_b128 v[168:171], v197 offset:5120
	ds_read_b128 v[172:175], v197 offset:6144
	ds_read_b128 v[176:179], v197 offset:7168
	global_load_lds_dwordx4 v[2:3], off
	v_lshl_add_u64 v[2:3], s[62:63], 0, v[186:187]
	s_add_i32 m0, s70, 0xe000
	s_nop 0
	global_load_lds_dwordx4 v[2:3], off
	s_waitcnt lgkmcnt(8)
	s_barrier
	s_waitcnt lgkmcnt(0)

	v_mfma_f32_16x16x32_bf16 v[124:127], v[132:135], v[148:151], v[124:127]
	v_mfma_f32_16x16x32_bf16 v[128:131], v[140:143], v[148:151], v[128:131]
	v_mfma_f32_16x16x32_bf16 v[108:111], v[132:135], v[156:159], v[108:111]
	v_mfma_f32_16x16x32_bf16 v[112:115], v[140:143], v[156:159], v[112:115]
	v_mfma_f32_16x16x32_bf16 v[92:95], v[132:135], v[164:167], v[92:95]
	v_mfma_f32_16x16x32_bf16 v[96:99], v[140:143], v[164:167], v[96:99]
	v_mfma_f32_16x16x32_bf16 v[76:79], v[132:135], v[172:175], v[76:79]
	v_mfma_f32_16x16x32_bf16 v[80:83], v[140:143], v[172:175], v[80:83]
	v_mfma_f32_16x16x32_bf16 v[124:127], v[136:139], v[152:155], v[124:127]
	v_mfma_f32_16x16x32_bf16 v[128:131], v[144:147], v[152:155], v[128:131]
	v_mfma_f32_16x16x32_bf16 v[108:111], v[136:139], v[160:163], v[108:111]
	v_mfma_f32_16x16x32_bf16 v[112:115], v[144:147], v[160:163], v[112:115]
	v_mfma_f32_16x16x32_bf16 v[92:95], v[136:139], v[168:171], v[92:95]
	v_mfma_f32_16x16x32_bf16 v[96:99], v[144:147], v[168:171], v[96:99]
	v_mfma_f32_16x16x32_bf16 v[76:79], v[136:139], v[176:179], v[76:79]
	v_mfma_f32_16x16x32_bf16 v[80:83], v[144:147], v[176:179], v[80:83]

	s_barrier
	s_add_i32 s3, s3, s67
	v_add_u32_e32 v1, s90, v196
	v_lshl_add_u64 v[214:215], s[64:65], 0, v[184:185]
	s_mov_b32 m0, s3
	ds_read_b128 v[198:201], v1
	ds_read_b128 v[202:205], v1 offset:1024
	ds_read_b128 v[206:209], v1 offset:2048
	ds_read_b128 v[210:213], v1 offset:3072
	global_load_lds_dwordx4 v[214:215], off
	v_lshl_add_u64 v[216:217], s[64:65], 0, v[188:189]
	s_add_i32 m0, s3, 0x2000
	s_nop 0
	global_load_lds_dwordx4 v[216:217], off
	s_barrier
	s_waitcnt lgkmcnt(0)

	v_mfma_f32_16x16x32_bf16 v[116:119], v[198:201], v[148:151], v[116:119]
	v_mfma_f32_16x16x32_bf16 v[120:123], v[206:209], v[148:151], v[120:123]
	v_mfma_f32_16x16x32_bf16 v[100:103], v[198:201], v[156:159], v[100:103]
	v_mfma_f32_16x16x32_bf16 v[104:107], v[206:209], v[156:159], v[104:107]
	v_mfma_f32_16x16x32_bf16 v[84:87], v[198:201], v[164:167], v[84:87]
	v_mfma_f32_16x16x32_bf16 v[88:91], v[206:209], v[164:167], v[88:91]
	v_mfma_f32_16x16x32_bf16 v[68:71], v[198:201], v[172:175], v[68:71]
	v_mfma_f32_16x16x32_bf16 v[72:75], v[206:209], v[172:175], v[72:75]
	v_mfma_f32_16x16x32_bf16 v[116:119], v[202:205], v[152:155], v[116:119]
	v_mfma_f32_16x16x32_bf16 v[120:123], v[210:213], v[152:155], v[120:123]
	v_mfma_f32_16x16x32_bf16 v[100:103], v[202:205], v[160:163], v[100:103]
	v_mfma_f32_16x16x32_bf16 v[104:107], v[210:213], v[160:163], v[104:107]
	v_mfma_f32_16x16x32_bf16 v[84:87], v[202:205], v[168:171], v[84:87]
	v_mfma_f32_16x16x32_bf16 v[88:91], v[210:213], v[168:171], v[88:91]
	v_mfma_f32_16x16x32_bf16 v[68:71], v[202:205], v[176:179], v[68:71]
	v_mfma_f32_16x16x32_bf16 v[72:75], v[210:213], v[176:179], v[72:75]

	s_mov_b32 m0, s70
	v_lshl_add_u64 v[218:219], s[60:61], 0, v[182:183]
	s_barrier
	ds_read_b128 v[148:151], v197 offset:16384
	ds_read_b128 v[152:155], v197 offset:17408
	ds_read_b128 v[156:159], v197 offset:18432
	ds_read_b128 v[160:163], v197 offset:19456
	ds_read_b128 v[164:167], v197 offset:20480
	ds_read_b128 v[168:171], v197 offset:21504
	ds_read_b128 v[172:175], v197 offset:22528
	ds_read_b128 v[176:179], v197 offset:23552
	global_load_lds_dwordx4 v[218:219], off
	v_lshl_add_u64 v[220:221], s[60:61], 0, v[186:187]
	s_mov_b32 m0, s71
	s_nop 0
	global_load_lds_dwordx4 v[220:221], off
	s_barrier
	s_waitcnt lgkmcnt(0)

	v_mfma_f32_16x16x32_bf16 v[60:63], v[132:135], v[148:151], v[60:63]
	v_mfma_f32_16x16x32_bf16 v[64:67], v[140:143], v[148:151], v[64:67]
	v_mfma_f32_16x16x32_bf16 v[44:47], v[132:135], v[156:159], v[44:47]
	v_mfma_f32_16x16x32_bf16 v[48:51], v[140:143], v[156:159], v[48:51]
	v_mfma_f32_16x16x32_bf16 v[28:31], v[132:135], v[164:167], v[28:31]
	v_mfma_f32_16x16x32_bf16 v[32:35], v[140:143], v[164:167], v[32:35]
	v_mfma_f32_16x16x32_bf16 v[12:15], v[132:135], v[172:175], v[12:15]
	v_mfma_f32_16x16x32_bf16 v[16:19], v[140:143], v[172:175], v[16:19]
	v_mfma_f32_16x16x32_bf16 v[60:63], v[136:139], v[152:155], v[60:63]
	v_mfma_f32_16x16x32_bf16 v[64:67], v[144:147], v[152:155], v[64:67]
	v_mfma_f32_16x16x32_bf16 v[44:47], v[136:139], v[160:163], v[44:47]
	v_mfma_f32_16x16x32_bf16 v[48:51], v[144:147], v[160:163], v[48:51]
	v_mfma_f32_16x16x32_bf16 v[28:31], v[136:139], v[168:171], v[28:31]
	v_mfma_f32_16x16x32_bf16 v[32:35], v[144:147], v[168:171], v[32:35]
	v_mfma_f32_16x16x32_bf16 v[12:15], v[136:139], v[176:179], v[12:15]
	v_mfma_f32_16x16x32_bf16 v[16:19], v[144:147], v[176:179], v[16:19]

	s_barrier
	s_add_u32 s62, s64, s8
	s_addc_u32 s63, s65, s9
	s_add_i32 s3, s90, s67
	v_lshl_add_u64 v[222:223], s[62:63], 0, v[184:185]
	s_mov_b32 m0, s3
	v_lshl_add_u64 v[224:225], s[62:63], 0, v[188:189]
	global_load_lds_dwordx4 v[222:223], off
	s_add_i32 m0, s3, 0x2000
	s_nop 0
	global_load_lds_dwordx4 v[224:225], off
	s_waitcnt vmcnt(6)
	s_barrier

	v_mfma_f32_16x16x32_bf16 v[52:55], v[198:201], v[148:151], v[52:55]
	v_mfma_f32_16x16x32_bf16 v[56:59], v[206:209], v[148:151], v[56:59]
	v_mfma_f32_16x16x32_bf16 v[36:39], v[198:201], v[156:159], v[36:39]
	v_mfma_f32_16x16x32_bf16 v[40:43], v[206:209], v[156:159], v[40:43]
	v_mfma_f32_16x16x32_bf16 v[20:23], v[198:201], v[164:167], v[20:23]
	v_mfma_f32_16x16x32_bf16 v[24:27], v[206:209], v[164:167], v[24:27]
	v_mfma_f32_16x16x32_bf16 v[2:5], v[198:201], v[172:175], v[4:7]
	v_mfma_f32_16x16x32_bf16 v[6:9], v[206:209], v[172:175], v[8:11]
	v_mfma_f32_16x16x32_bf16 v[52:55], v[202:205], v[152:155], v[52:55]
	v_mfma_f32_16x16x32_bf16 v[56:59], v[210:213], v[152:155], v[56:59]
	v_mfma_f32_16x16x32_bf16 v[36:39], v[202:205], v[160:163], v[36:39]
	v_mfma_f32_16x16x32_bf16 v[40:43], v[210:213], v[160:163], v[40:43]
	v_mfma_f32_16x16x32_bf16 v[20:23], v[202:205], v[168:171], v[20:23]
	v_mfma_f32_16x16x32_bf16 v[24:27], v[210:213], v[168:171], v[24:27]
	v_mfma_f32_16x16x32_bf16 v[2:5], v[202:205], v[176:179], v[2:5]
	v_mfma_f32_16x16x32_bf16 v[8:11], v[210:213], v[176:179], v[6:9]

	s_add_i32 s3, 0, 0x18000
	v_add_u32_e32 v1, s3, v196
	s_barrier
	ds_read_b128 v[132:135], v1
	ds_read_b128 v[136:139], v1 offset:1024
	ds_read_b128 v[140:143], v1 offset:2048
	ds_read_b128 v[144:147], v1 offset:3072
	s_add_u32 s60, s60, 0x20000
	s_addc_u32 s61, s61, 0
	s_mov_b32 m0, s72
	v_lshl_add_u64 v[6:7], s[60:61], 0, v[182:183]
	ds_read_b128 v[148:151], v197 offset:32768
	ds_read_b128 v[152:155], v197 offset:33792
	ds_read_b128 v[156:159], v197 offset:34816
	ds_read_b128 v[160:163], v197 offset:35840
	ds_read_b128 v[164:167], v197 offset:36864
	ds_read_b128 v[168:171], v197 offset:37888
	ds_read_b128 v[172:175], v197 offset:38912
	ds_read_b128 v[176:179], v197 offset:39936
	global_load_lds_dwordx4 v[6:7], off
	v_lshl_add_u64 v[6:7], s[60:61], 0, v[186:187]
	s_mov_b32 m0, s73
	s_nop 0
	global_load_lds_dwordx4 v[6:7], off
	s_waitcnt lgkmcnt(8)
	s_barrier
	s_waitcnt lgkmcnt(0)

	v_mfma_f32_16x16x32_bf16 v[124:127], v[132:135], v[148:151], v[124:127]
	v_mfma_f32_16x16x32_bf16 v[128:131], v[140:143], v[148:151], v[128:131]
	v_mfma_f32_16x16x32_bf16 v[108:111], v[132:135], v[156:159], v[108:111]
	v_mfma_f32_16x16x32_bf16 v[112:115], v[140:143], v[156:159], v[112:115]
	v_mfma_f32_16x16x32_bf16 v[92:95], v[132:135], v[164:167], v[92:95]
	v_mfma_f32_16x16x32_bf16 v[96:99], v[140:143], v[164:167], v[96:99]
	v_mfma_f32_16x16x32_bf16 v[76:79], v[132:135], v[172:175], v[76:79]
	v_mfma_f32_16x16x32_bf16 v[80:83], v[140:143], v[172:175], v[80:83]
	v_mfma_f32_16x16x32_bf16 v[124:127], v[136:139], v[152:155], v[124:127]
	v_mfma_f32_16x16x32_bf16 v[128:131], v[144:147], v[152:155], v[128:131]
	v_mfma_f32_16x16x32_bf16 v[108:111], v[136:139], v[160:163], v[108:111]
	v_mfma_f32_16x16x32_bf16 v[112:115], v[144:147], v[160:163], v[112:115]
	v_mfma_f32_16x16x32_bf16 v[92:95], v[136:139], v[168:171], v[92:95]
	v_mfma_f32_16x16x32_bf16 v[96:99], v[144:147], v[168:171], v[96:99]
	v_mfma_f32_16x16x32_bf16 v[76:79], v[136:139], v[176:179], v[76:79]
	v_mfma_f32_16x16x32_bf16 v[80:83], v[144:147], v[176:179], v[80:83]

	s_barrier
	s_add_i32 s12, 0, 0x1c000
	s_add_i32 s3, s3, s67
	v_add_u32_e32 v1, s12, v196
	v_lshl_add_u64 v[6:7], v[214:215], 0, s[14:15]
	s_mov_b32 m0, s3
	ds_read_b128 v[198:201], v1
	ds_read_b128 v[202:205], v1 offset:1024
	ds_read_b128 v[206:209], v1 offset:2048
	ds_read_b128 v[210:213], v1 offset:3072
	global_load_lds_dwordx4 v[6:7], off
	v_lshl_add_u64 v[6:7], v[216:217], 0, s[14:15]
	s_add_i32 m0, s3, 0x2000
	s_nop 0
	global_load_lds_dwordx4 v[6:7], off
	s_barrier
	s_waitcnt lgkmcnt(0)

	v_mfma_f32_16x16x32_bf16 v[116:119], v[198:201], v[148:151], v[116:119]
	v_mfma_f32_16x16x32_bf16 v[120:123], v[206:209], v[148:151], v[120:123]
	v_mfma_f32_16x16x32_bf16 v[100:103], v[198:201], v[156:159], v[100:103]
	v_mfma_f32_16x16x32_bf16 v[104:107], v[206:209], v[156:159], v[104:107]
	v_mfma_f32_16x16x32_bf16 v[84:87], v[198:201], v[164:167], v[84:87]
	v_mfma_f32_16x16x32_bf16 v[88:91], v[206:209], v[164:167], v[88:91]
	v_mfma_f32_16x16x32_bf16 v[68:71], v[198:201], v[172:175], v[68:71]
	v_mfma_f32_16x16x32_bf16 v[72:75], v[206:209], v[172:175], v[72:75]
	v_mfma_f32_16x16x32_bf16 v[116:119], v[202:205], v[152:155], v[116:119]
	v_mfma_f32_16x16x32_bf16 v[120:123], v[210:213], v[152:155], v[120:123]
	v_mfma_f32_16x16x32_bf16 v[100:103], v[202:205], v[160:163], v[100:103]
	v_mfma_f32_16x16x32_bf16 v[104:107], v[210:213], v[160:163], v[104:107]
	v_mfma_f32_16x16x32_bf16 v[84:87], v[202:205], v[168:171], v[84:87]
	v_mfma_f32_16x16x32_bf16 v[88:91], v[210:213], v[168:171], v[88:91]
	v_mfma_f32_16x16x32_bf16 v[68:71], v[202:205], v[176:179], v[68:71]
	v_mfma_f32_16x16x32_bf16 v[72:75], v[210:213], v[176:179], v[72:75]

	s_mov_b32 m0, s76
	v_lshl_add_u64 v[6:7], v[218:219], 0, s[14:15]
	s_barrier
	ds_read_b128 v[148:151], v197 offset:49152
	ds_read_b128 v[152:155], v197 offset:50176
	ds_read_b128 v[156:159], v197 offset:51200
	ds_read_b128 v[160:163], v197 offset:52224
	ds_read_b128 v[164:167], v197 offset:53248
	ds_read_b128 v[168:171], v197 offset:54272
	ds_read_b128 v[172:175], v197 offset:55296
	ds_read_b128 v[176:179], v197 offset:56320
	global_load_lds_dwordx4 v[6:7], off
	v_lshl_add_u64 v[6:7], v[220:221], 0, s[14:15]
	s_mov_b32 m0, s77
	s_nop 0
	global_load_lds_dwordx4 v[6:7], off
	s_barrier
	s_waitcnt lgkmcnt(0)

	v_mfma_f32_16x16x32_bf16 v[60:63], v[132:135], v[148:151], v[60:63]
	v_mfma_f32_16x16x32_bf16 v[64:67], v[140:143], v[148:151], v[64:67]
	v_mfma_f32_16x16x32_bf16 v[44:47], v[132:135], v[156:159], v[44:47]
	v_mfma_f32_16x16x32_bf16 v[48:51], v[140:143], v[156:159], v[48:51]
	v_mfma_f32_16x16x32_bf16 v[28:31], v[132:135], v[164:167], v[28:31]
	v_mfma_f32_16x16x32_bf16 v[32:35], v[140:143], v[164:167], v[32:35]
	v_mfma_f32_16x16x32_bf16 v[12:15], v[132:135], v[172:175], v[12:15]
	v_mfma_f32_16x16x32_bf16 v[16:19], v[140:143], v[172:175], v[16:19]
	v_mfma_f32_16x16x32_bf16 v[60:63], v[136:139], v[152:155], v[60:63]
	v_mfma_f32_16x16x32_bf16 v[64:67], v[144:147], v[152:155], v[64:67]
	v_mfma_f32_16x16x32_bf16 v[44:47], v[136:139], v[160:163], v[44:47]
	v_mfma_f32_16x16x32_bf16 v[48:51], v[144:147], v[160:163], v[48:51]
	v_mfma_f32_16x16x32_bf16 v[28:31], v[136:139], v[168:171], v[28:31]
	v_mfma_f32_16x16x32_bf16 v[32:35], v[144:147], v[168:171], v[32:35]
	v_mfma_f32_16x16x32_bf16 v[12:15], v[136:139], v[176:179], v[12:15]
	v_mfma_f32_16x16x32_bf16 v[16:19], v[144:147], v[176:179], v[16:19]

	s_barrier
	s_add_i32 s3, s12, s67
	v_lshl_add_u64 v[6:7], v[222:223], 0, s[14:15]
	s_mov_b32 m0, s3
	s_nop 0
	global_load_lds_dwordx4 v[6:7], off
	v_lshl_add_u64 v[6:7], v[224:225], 0, s[14:15]
	s_add_i32 m0, s3, 0x2000
	s_nop 0
	global_load_lds_dwordx4 v[6:7], off
	s_waitcnt vmcnt(6)
	s_barrier

	v_mfma_f32_16x16x32_bf16 v[52:55], v[198:201], v[148:151], v[52:55]
	v_mfma_f32_16x16x32_bf16 v[56:59], v[206:209], v[148:151], v[56:59]
	v_mfma_f32_16x16x32_bf16 v[36:39], v[198:201], v[156:159], v[36:39]
	v_mfma_f32_16x16x32_bf16 v[40:43], v[206:209], v[156:159], v[40:43]
	v_mfma_f32_16x16x32_bf16 v[20:23], v[198:201], v[164:167], v[20:23]
	v_mfma_f32_16x16x32_bf16 v[24:27], v[206:209], v[164:167], v[24:27]
	v_mfma_f32_16x16x32_bf16 v[2:5], v[198:201], v[172:175], v[2:5]
	v_mfma_f32_16x16x32_bf16 v[8:11], v[206:209], v[172:175], v[8:11]
	v_mfma_f32_16x16x32_bf16 v[52:55], v[202:205], v[152:155], v[52:55]
	v_mfma_f32_16x16x32_bf16 v[56:59], v[210:213], v[152:155], v[56:59]
	v_mfma_f32_16x16x32_bf16 v[36:39], v[202:205], v[160:163], v[36:39]
	v_mfma_f32_16x16x32_bf16 v[40:43], v[210:213], v[160:163], v[40:43]
	v_mfma_f32_16x16x32_bf16 v[20:23], v[202:205], v[168:171], v[20:23]
	v_mfma_f32_16x16x32_bf16 v[24:27], v[210:213], v[168:171], v[24:27]
	v_mfma_f32_16x16x32_bf16 v[4:7], v[202:205], v[176:179], v[2:5]
	v_mfma_f32_16x16x32_bf16 v[8:11], v[210:213], v[176:179], v[8:11]

	s_add_u32 s58, s58, 0x100
	s_addc_u32 s59, s59, 0
	s_add_u32 s96, s96, 0x100
	s_addc_u32 s97, s97, 0
	s_cmp_ge_i32 s68, s78
	s_barrier
	s_cbranch_scc1 .LBB0_667

.LBB0_766:
	ds_read_b128 v[128:131], v215
	ds_read_b128 v[132:135], v215 offset:1024
	ds_read_b128 v[136:139], v215 offset:2048
	ds_read_b128 v[140:143], v215 offset:3072
	s_add_i32 s62, s24, 2
	s_add_u32 s26, s0, 0x80
	s_addc_u32 s25, s1, 0
	s_cmp_eq_u32 s51, s24
	s_cselect_b32 s24, s20, s26
	s_cselect_b32 s25, s21, s25
	s_cselect_b32 s27, s7, s61
	s_cselect_b32 s26, s6, s60
	v_lshl_add_u64 v[194:195], s[0:1], 0, v[186:187]
	s_add_i32 m0, s41, 0xc000
	ds_read_b128 v[144:147], v216
	ds_read_b128 v[148:151], v216 offset:1024
	ds_read_b128 v[152:155], v216 offset:2048
	ds_read_b128 v[156:159], v216 offset:3072
	ds_read_b128 v[160:163], v216 offset:4096
	ds_read_b128 v[164:167], v216 offset:5120
	ds_read_b128 v[168:171], v216 offset:6144
	ds_read_b128 v[172:175], v216 offset:7168
	global_load_lds_dwordx4 v[194:195], off
	v_lshl_add_u64 v[194:195], s[0:1], 0, v[188:189]
	s_add_i32 m0, s41, 0xe000
	s_nop 0
	global_load_lds_dwordx4 v[194:195], off
	s_waitcnt lgkmcnt(8)
	s_barrier
	s_waitcnt lgkmcnt(0)

	v_mfma_f32_16x16x32_bf16 v[124:127], v[128:131], v[144:147], v[124:127]
	v_mfma_f32_16x16x32_bf16 v[120:123], v[136:139], v[144:147], v[120:123]
	v_mfma_f32_16x16x32_bf16 v[108:111], v[128:131], v[152:155], v[108:111]
	v_mfma_f32_16x16x32_bf16 v[104:107], v[136:139], v[152:155], v[104:107]
	v_mfma_f32_16x16x32_bf16 v[92:95], v[128:131], v[160:163], v[92:95]
	v_mfma_f32_16x16x32_bf16 v[88:91], v[136:139], v[160:163], v[88:91]
	v_mfma_f32_16x16x32_bf16 v[76:79], v[128:131], v[168:171], v[76:79]
	v_mfma_f32_16x16x32_bf16 v[72:75], v[136:139], v[168:171], v[72:75]
	v_mfma_f32_16x16x32_bf16 v[124:127], v[132:135], v[148:151], v[124:127]
	v_mfma_f32_16x16x32_bf16 v[120:123], v[140:143], v[148:151], v[120:123]
	v_mfma_f32_16x16x32_bf16 v[108:111], v[132:135], v[156:159], v[108:111]
	v_mfma_f32_16x16x32_bf16 v[104:107], v[140:143], v[156:159], v[104:107]
	v_mfma_f32_16x16x32_bf16 v[92:95], v[132:135], v[164:167], v[92:95]
	v_mfma_f32_16x16x32_bf16 v[88:91], v[140:143], v[164:167], v[88:91]
	v_mfma_f32_16x16x32_bf16 v[76:79], v[132:135], v[172:175], v[76:79]
	v_mfma_f32_16x16x32_bf16 v[72:75], v[140:143], v[172:175], v[72:75]

	s_barrier
	s_add_i32 s63, s55, s40
	v_lshl_add_u64 v[210:211], s[26:27], 0, v[178:179]
	s_mov_b32 m0, s63
	ds_read_b128 v[194:197], v217
	ds_read_b128 v[198:201], v217 offset:1024
	ds_read_b128 v[202:205], v217 offset:2048
	ds_read_b128 v[206:209], v217 offset:3072
	global_load_lds_dwordx4 v[210:211], off
	v_lshl_add_u64 v[218:219], s[26:27], 0, v[184:185]
	s_add_i32 m0, s63, 0x2000
	s_nop 0
	global_load_lds_dwordx4 v[218:219], off
	s_barrier
	s_waitcnt lgkmcnt(0)

	v_mfma_f32_16x16x32_bf16 v[116:119], v[194:197], v[144:147], v[116:119]
	v_mfma_f32_16x16x32_bf16 v[112:115], v[202:205], v[144:147], v[112:115]
	v_mfma_f32_16x16x32_bf16 v[100:103], v[194:197], v[152:155], v[100:103]
	v_mfma_f32_16x16x32_bf16 v[96:99], v[202:205], v[152:155], v[96:99]
	v_mfma_f32_16x16x32_bf16 v[84:87], v[194:197], v[160:163], v[84:87]
	v_mfma_f32_16x16x32_bf16 v[80:83], v[202:205], v[160:163], v[80:83]
	v_mfma_f32_16x16x32_bf16 v[68:71], v[194:197], v[168:171], v[68:71]
	v_mfma_f32_16x16x32_bf16 v[64:67], v[202:205], v[168:171], v[64:67]
	v_mfma_f32_16x16x32_bf16 v[116:119], v[198:201], v[148:151], v[116:119]
	v_mfma_f32_16x16x32_bf16 v[112:115], v[206:209], v[148:151], v[112:115]
	v_mfma_f32_16x16x32_bf16 v[100:103], v[198:201], v[156:159], v[100:103]
	v_mfma_f32_16x16x32_bf16 v[96:99], v[206:209], v[156:159], v[96:99]
	v_mfma_f32_16x16x32_bf16 v[84:87], v[198:201], v[164:167], v[84:87]
	v_mfma_f32_16x16x32_bf16 v[80:83], v[206:209], v[164:167], v[80:83]
	v_mfma_f32_16x16x32_bf16 v[68:71], v[198:201], v[172:175], v[68:71]
	v_mfma_f32_16x16x32_bf16 v[64:67], v[206:209], v[172:175], v[64:67]

	s_mov_b32 m0, s41
	v_lshl_add_u64 v[220:221], s[24:25], 0, v[176:177]
	s_barrier
	ds_read_b128 v[144:147], v216 offset:16384
	ds_read_b128 v[148:151], v216 offset:17408
	ds_read_b128 v[152:155], v216 offset:18432
	ds_read_b128 v[156:159], v216 offset:19456
	ds_read_b128 v[160:163], v216 offset:20480
	ds_read_b128 v[164:167], v216 offset:21504
	ds_read_b128 v[168:171], v216 offset:22528
	ds_read_b128 v[172:175], v216 offset:23552
	global_load_lds_dwordx4 v[220:221], off
	v_lshl_add_u64 v[222:223], s[24:25], 0, v[182:183]
	s_mov_b32 m0, s42
	s_nop 0
	global_load_lds_dwordx4 v[222:223], off
	s_barrier
	s_waitcnt lgkmcnt(0)

	v_mfma_f32_16x16x32_bf16 v[60:63], v[128:131], v[144:147], v[60:63]
	v_mfma_f32_16x16x32_bf16 v[56:59], v[136:139], v[144:147], v[56:59]
	v_mfma_f32_16x16x32_bf16 v[44:47], v[128:131], v[152:155], v[44:47]
	v_mfma_f32_16x16x32_bf16 v[40:43], v[136:139], v[152:155], v[40:43]
	v_mfma_f32_16x16x32_bf16 v[28:31], v[128:131], v[160:163], v[28:31]
	v_mfma_f32_16x16x32_bf16 v[24:27], v[136:139], v[160:163], v[24:27]
	v_mfma_f32_16x16x32_bf16 v[12:15], v[128:131], v[168:171], v[12:15]
	v_mfma_f32_16x16x32_bf16 v[8:11], v[136:139], v[168:171], v[8:11]
	v_mfma_f32_16x16x32_bf16 v[60:63], v[132:135], v[148:151], v[60:63]
	v_mfma_f32_16x16x32_bf16 v[56:59], v[140:143], v[148:151], v[56:59]
	v_mfma_f32_16x16x32_bf16 v[44:47], v[132:135], v[156:159], v[44:47]
	v_mfma_f32_16x16x32_bf16 v[40:43], v[140:143], v[156:159], v[40:43]
	v_mfma_f32_16x16x32_bf16 v[28:31], v[132:135], v[164:167], v[28:31]
	v_mfma_f32_16x16x32_bf16 v[24:27], v[140:143], v[164:167], v[24:27]
	v_mfma_f32_16x16x32_bf16 v[12:15], v[132:135], v[172:175], v[12:15]
	v_mfma_f32_16x16x32_bf16 v[8:11], v[140:143], v[172:175], v[8:11]

	s_barrier
	s_add_u32 s26, s26, s8
	s_addc_u32 s27, s27, s9
	s_add_i32 s63, s56, s40
	v_lshl_add_u64 v[224:225], s[26:27], 0, v[178:179]
	s_mov_b32 m0, s63
	v_lshl_add_u64 v[226:227], s[26:27], 0, v[184:185]
	global_load_lds_dwordx4 v[224:225], off
	s_add_i32 m0, s63, 0x2000
	s_nop 0
	global_load_lds_dwordx4 v[226:227], off
	s_waitcnt vmcnt(6)
	s_barrier

	v_mfma_f32_16x16x32_bf16 v[52:55], v[194:197], v[144:147], v[52:55]
	v_mfma_f32_16x16x32_bf16 v[48:51], v[202:205], v[144:147], v[48:51]
	v_mfma_f32_16x16x32_bf16 v[36:39], v[194:197], v[152:155], v[36:39]
	v_mfma_f32_16x16x32_bf16 v[32:35], v[202:205], v[152:155], v[32:35]
	v_mfma_f32_16x16x32_bf16 v[20:23], v[194:197], v[160:163], v[20:23]
	v_mfma_f32_16x16x32_bf16 v[16:19], v[202:205], v[160:163], v[16:19]
	v_mfma_f32_16x16x32_bf16 v[4:7], v[194:197], v[168:171], v[4:7]
	v_mfma_f32_16x16x32_bf16 v[0:3], v[202:205], v[168:171], v[0:3]
	v_mfma_f32_16x16x32_bf16 v[52:55], v[198:201], v[148:151], v[52:55]
	v_mfma_f32_16x16x32_bf16 v[48:51], v[206:209], v[148:151], v[48:51]
	v_mfma_f32_16x16x32_bf16 v[36:39], v[198:201], v[156:159], v[36:39]
	v_mfma_f32_16x16x32_bf16 v[32:35], v[206:209], v[156:159], v[32:35]
	v_mfma_f32_16x16x32_bf16 v[20:23], v[198:201], v[164:167], v[20:23]
	v_mfma_f32_16x16x32_bf16 v[16:19], v[206:209], v[164:167], v[16:19]
	v_mfma_f32_16x16x32_bf16 v[4:7], v[198:201], v[172:175], v[4:7]
	v_mfma_f32_16x16x32_bf16 v[0:3], v[206:209], v[172:175], v[0:3]

	s_add_i32 s26, 0, 0x18000
	v_add_u32_e32 v140, s26, v214
	s_barrier
	ds_read_b128 v[128:131], v140
	ds_read_b128 v[132:135], v140 offset:1024
	ds_read_b128 v[136:139], v140 offset:2048
	ds_read_b128 v[140:143], v140 offset:3072
	s_add_u32 s24, s24, s8
	s_addc_u32 s25, s25, s9
	s_mov_b32 m0, s43
	v_lshl_add_u64 v[194:195], s[24:25], 0, v[176:177]
	ds_read_b128 v[144:147], v216 offset:32768
	ds_read_b128 v[148:151], v216 offset:33792
	ds_read_b128 v[152:155], v216 offset:34816
	ds_read_b128 v[156:159], v216 offset:35840
	ds_read_b128 v[160:163], v216 offset:36864
	ds_read_b128 v[164:167], v216 offset:37888
	ds_read_b128 v[168:171], v216 offset:38912
	ds_read_b128 v[172:175], v216 offset:39936
	global_load_lds_dwordx4 v[194:195], off
	v_lshl_add_u64 v[194:195], s[24:25], 0, v[182:183]
	s_mov_b32 m0, s44
	s_nop 0
	global_load_lds_dwordx4 v[194:195], off
	s_waitcnt lgkmcnt(8)
	s_barrier
	s_waitcnt lgkmcnt(0)

	v_mfma_f32_16x16x32_bf16 v[124:127], v[128:131], v[144:147], v[124:127]
	v_mfma_f32_16x16x32_bf16 v[120:123], v[136:139], v[144:147], v[120:123]
	v_mfma_f32_16x16x32_bf16 v[108:111], v[128:131], v[152:155], v[108:111]
	v_mfma_f32_16x16x32_bf16 v[104:107], v[136:139], v[152:155], v[104:107]
	v_mfma_f32_16x16x32_bf16 v[92:95], v[128:131], v[160:163], v[92:95]
	v_mfma_f32_16x16x32_bf16 v[88:91], v[136:139], v[160:163], v[88:91]
	v_mfma_f32_16x16x32_bf16 v[76:79], v[128:131], v[168:171], v[76:79]
	v_mfma_f32_16x16x32_bf16 v[72:75], v[136:139], v[168:171], v[72:75]
	v_mfma_f32_16x16x32_bf16 v[124:127], v[132:135], v[148:151], v[124:127]
	v_mfma_f32_16x16x32_bf16 v[120:123], v[140:143], v[148:151], v[120:123]
	v_mfma_f32_16x16x32_bf16 v[108:111], v[132:135], v[156:159], v[108:111]
	v_mfma_f32_16x16x32_bf16 v[104:107], v[140:143], v[156:159], v[104:107]
	v_mfma_f32_16x16x32_bf16 v[92:95], v[132:135], v[164:167], v[92:95]
	v_mfma_f32_16x16x32_bf16 v[88:91], v[140:143], v[164:167], v[88:91]
	v_mfma_f32_16x16x32_bf16 v[76:79], v[132:135], v[172:175], v[76:79]
	v_mfma_f32_16x16x32_bf16 v[72:75], v[140:143], v[172:175], v[72:75]

	s_barrier
	s_add_i32 s24, 0, 0x1c000
	s_add_i32 s25, s26, s40
	v_add_u32_e32 v206, s24, v214
	v_lshl_add_u64 v[210:211], v[210:211], 0, s[12:13]
	s_mov_b32 m0, s25
	ds_read_b128 v[194:197], v206
	ds_read_b128 v[198:201], v206 offset:1024
	ds_read_b128 v[202:205], v206 offset:2048
	ds_read_b128 v[206:209], v206 offset:3072
	global_load_lds_dwordx4 v[210:211], off
	v_lshl_add_u64 v[210:211], v[218:219], 0, s[12:13]
	s_add_i32 m0, s25, 0x2000
	s_nop 0
	global_load_lds_dwordx4 v[210:211], off
	s_barrier
	s_waitcnt lgkmcnt(0)

	v_mfma_f32_16x16x32_bf16 v[116:119], v[194:197], v[144:147], v[116:119]
	v_mfma_f32_16x16x32_bf16 v[112:115], v[202:205], v[144:147], v[112:115]
	v_mfma_f32_16x16x32_bf16 v[100:103], v[194:197], v[152:155], v[100:103]
	v_mfma_f32_16x16x32_bf16 v[96:99], v[202:205], v[152:155], v[96:99]
	v_mfma_f32_16x16x32_bf16 v[84:87], v[194:197], v[160:163], v[84:87]
	v_mfma_f32_16x16x32_bf16 v[80:83], v[202:205], v[160:163], v[80:83]
	v_mfma_f32_16x16x32_bf16 v[68:71], v[194:197], v[168:171], v[68:71]
	v_mfma_f32_16x16x32_bf16 v[64:67], v[202:205], v[168:171], v[64:67]
	v_mfma_f32_16x16x32_bf16 v[116:119], v[198:201], v[148:151], v[116:119]
	v_mfma_f32_16x16x32_bf16 v[112:115], v[206:209], v[148:151], v[112:115]
	v_mfma_f32_16x16x32_bf16 v[100:103], v[198:201], v[156:159], v[100:103]
	v_mfma_f32_16x16x32_bf16 v[96:99], v[206:209], v[156:159], v[96:99]
	v_mfma_f32_16x16x32_bf16 v[84:87], v[198:201], v[164:167], v[84:87]
	v_mfma_f32_16x16x32_bf16 v[80:83], v[206:209], v[164:167], v[80:83]
	v_mfma_f32_16x16x32_bf16 v[68:71], v[198:201], v[172:175], v[68:71]
	v_mfma_f32_16x16x32_bf16 v[64:67], v[206:209], v[172:175], v[64:67]

	s_mov_b32 m0, s46
	v_lshl_add_u64 v[210:211], v[220:221], 0, s[12:13]
	s_barrier
	ds_read_b128 v[144:147], v216 offset:49152
	ds_read_b128 v[148:151], v216 offset:50176
	ds_read_b128 v[152:155], v216 offset:51200
	ds_read_b128 v[156:159], v216 offset:52224
	ds_read_b128 v[160:163], v216 offset:53248
	ds_read_b128 v[164:167], v216 offset:54272
	ds_read_b128 v[168:171], v216 offset:55296
	ds_read_b128 v[172:175], v216 offset:56320
	global_load_lds_dwordx4 v[210:211], off
	v_lshl_add_u64 v[210:211], v[222:223], 0, s[12:13]
	s_mov_b32 m0, s47
	s_nop 0
	global_load_lds_dwordx4 v[210:211], off
	s_barrier
	s_waitcnt lgkmcnt(0)

	v_mfma_f32_16x16x32_bf16 v[60:63], v[128:131], v[144:147], v[60:63]
	v_mfma_f32_16x16x32_bf16 v[56:59], v[136:139], v[144:147], v[56:59]
	v_mfma_f32_16x16x32_bf16 v[44:47], v[128:131], v[152:155], v[44:47]
	v_mfma_f32_16x16x32_bf16 v[40:43], v[136:139], v[152:155], v[40:43]
	v_mfma_f32_16x16x32_bf16 v[28:31], v[128:131], v[160:163], v[28:31]
	v_mfma_f32_16x16x32_bf16 v[24:27], v[136:139], v[160:163], v[24:27]
	v_mfma_f32_16x16x32_bf16 v[12:15], v[128:131], v[168:171], v[12:15]
	v_mfma_f32_16x16x32_bf16 v[8:11], v[136:139], v[168:171], v[8:11]
	v_mfma_f32_16x16x32_bf16 v[60:63], v[132:135], v[148:151], v[60:63]
	v_mfma_f32_16x16x32_bf16 v[56:59], v[140:143], v[148:151], v[56:59]
	v_mfma_f32_16x16x32_bf16 v[44:47], v[132:135], v[156:159], v[44:47]
	v_mfma_f32_16x16x32_bf16 v[40:43], v[140:143], v[156:159], v[40:43]
	v_mfma_f32_16x16x32_bf16 v[28:31], v[132:135], v[164:167], v[28:31]
	v_mfma_f32_16x16x32_bf16 v[24:27], v[140:143], v[164:167], v[24:27]
	v_mfma_f32_16x16x32_bf16 v[12:15], v[132:135], v[172:175], v[12:15]
	v_mfma_f32_16x16x32_bf16 v[8:11], v[140:143], v[172:175], v[8:11]

	s_barrier
	s_add_i32 s24, s24, s40
	v_lshl_add_u64 v[128:129], v[224:225], 0, s[12:13]
	s_mov_b32 m0, s24
	s_nop 0
	global_load_lds_dwordx4 v[128:129], off
	v_lshl_add_u64 v[128:129], v[226:227], 0, s[12:13]
	s_add_i32 m0, s24, 0x2000
	s_nop 0
	global_load_lds_dwordx4 v[128:129], off
	s_waitcnt vmcnt(6)
	s_barrier

	v_mfma_f32_16x16x32_bf16 v[52:55], v[194:197], v[144:147], v[52:55]
	v_mfma_f32_16x16x32_bf16 v[48:51], v[202:205], v[144:147], v[48:51]
	v_mfma_f32_16x16x32_bf16 v[36:39], v[194:197], v[152:155], v[36:39]
	v_mfma_f32_16x16x32_bf16 v[32:35], v[202:205], v[152:155], v[32:35]
	v_mfma_f32_16x16x32_bf16 v[20:23], v[194:197], v[160:163], v[20:23]
	v_mfma_f32_16x16x32_bf16 v[16:19], v[202:205], v[160:163], v[16:19]
	v_mfma_f32_16x16x32_bf16 v[4:7], v[194:197], v[168:171], v[4:7]
	v_mfma_f32_16x16x32_bf16 v[0:3], v[202:205], v[168:171], v[0:3]
	v_mfma_f32_16x16x32_bf16 v[52:55], v[198:201], v[148:151], v[52:55]
	v_mfma_f32_16x16x32_bf16 v[48:51], v[206:209], v[148:151], v[48:51]
	v_mfma_f32_16x16x32_bf16 v[36:39], v[198:201], v[156:159], v[36:39]
	v_mfma_f32_16x16x32_bf16 v[32:35], v[206:209], v[156:159], v[32:35]
	v_mfma_f32_16x16x32_bf16 v[20:23], v[198:201], v[164:167], v[20:23]
	v_mfma_f32_16x16x32_bf16 v[16:19], v[206:209], v[164:167], v[16:19]
	v_mfma_f32_16x16x32_bf16 v[4:7], v[198:201], v[172:175], v[4:7]
	v_mfma_f32_16x16x32_bf16 v[0:3], v[206:209], v[172:175], v[0:3]

	s_add_u32 s0, s0, 0x100
	s_addc_u32 s1, s1, 0
	s_add_u32 s60, s60, 0x100
	s_addc_u32 s61, s61, 0
	s_cmp_ge_i32 s62, s48
	s_mov_b32 s24, s62
	s_barrier
	s_cbranch_scc0 .LBB0_766
